# plus: 3.5us stagger of half the workgroups at the attention phase entry
# speedup vs baseline: 1.0129x; 1.0110x over previous
; DI void phase_attn1(const Params& p, char* smem) {
;   const int G = gridDim.x;
;   for (int round = 0; round * G < 512; ++round) {
;     const int j = (round & 1) ? (G - 1 - (int)blockIdx.x) : (int)blockIdx.x;
;     const int t = round * G + j;
;     if (t >= 512) continue;
;     const int qt = 15 - (t >> 5), bh = t & 31;
;     mla_item(p, bh >> 3, bh & 7, qt, smem);
;   }
.LBB0_1361:
	s_or_b64 exec, exec, s[0:1]
	s_not_b32 s0, s84
	s_add_i32 s27, s96, s0
	s_add_u32 s24, s22, 0x154c0000
	s_addc_u32 s25, s23, 0
	s_add_u32 s33, s22, 0x184c0000
	s_addc_u32 s40, s23, 0
	s_add_u32 s41, s22, 0x1a4c0000
	s_addc_u32 s44, s23, 0
	s_add_u32 s45, s22, 0x1a6c0000
	s_addc_u32 s46, s23, 0
	s_add_u32 s28, s22, 0x40c0000
	s_movk_i32 s34, 0xff00
	s_addc_u32 s29, s23, 0
	s_mov_b32 s31, 0
	s_movk_i32 s47, 0xc00
	v_mov_b32_e32 v0, 0
	s_mov_b32 s48, 0x2aaaaaab
	s_mov_b32 s35, -1
	s_movk_i32 s49, 0x190
	s_movk_i32 s50, 0x88
	s_movk_i32 s51, 0x6400
	s_mov_b32 s52, 0xf149f2ca
	s_mov_b32 s53, 0x3dd53b94
	s_mov_b32 s54, 0x41000000
	s_mov_b64 s[36:37], 0x20000
	s_mov_b64 s[38:39], 0x2000
	s_movk_i32 s55, 0x3300
	s_mov_b64 s[42:43], 0x80c0a00
	s_mov_b32 s56, 0x80c0000
	v_mov_b32_e32 v199, 0xf149f2ca
	v_mbcnt_hi_u32_b32 v198, -1, v207
	s_mov_b32 s0, 0
	s_mov_b32 s57, 0
	s_bitcmp1_b32 s84, 3
	s_cbranch_scc0 .Lstag_10
	s_sleep 127
.Lstag_10:
	s_waitcnt lgkmcnt(0)
	s_barrier
	s_branch .LBB0_1365
